# stack22 + seams: unused TOPGEN add dropped (last leader no longer waits for it) and leader's final wait relaxed to vmcnt(1) (release atomic left in flight)
# speedup vs baseline: 1.0005x; 1.0005x over previous
.LBB0_116:
	s_or_b64 exec, exec, s[10:11]
	v_cvt_f32_u32_e32 v5, v2
	s_waitcnt vmcnt(0)
	v_readfirstlane_b32 s0, v4
	s_add_u32 s10, s76, 0x3500
	s_addc_u32 s11, s77, 0
	s_add_u32 s98, s76, 0x3400
	s_addc_u32 s99, s77, 0
	v_rcp_iflag_f32_e32 v5, v5
	v_add_u32_e32 v3, s0, v3
	v_add_u32_e32 v6, 1, v3
	s_mov_b64 s[12:13], 0
	v_mul_f32_e32 v4, 0x4f7ffffe, v5
	v_cvt_u32_f32_e32 v4, v4
	v_sub_u32_e32 v5, 0, v2
	v_mul_lo_u32 v5, v5, v4
	v_mul_hi_u32 v5, v4, v5
	v_add_u32_e32 v4, v4, v5
	v_mul_hi_u32 v4, v3, v4
	v_mul_lo_u32 v5, v4, v2
	v_sub_u32_e32 v3, v3, v5
	v_add_u32_e32 v7, 1, v4
	v_cmp_ge_u32_e32 vcc, v3, v2
	v_sub_u32_e32 v5, v3, v2
	s_nop 0
	v_cndmask_b32_e32 v4, v4, v7, vcc
	v_cndmask_b32_e32 v3, v3, v5, vcc
	v_add_u32_e32 v5, 1, v4
	v_cmp_ge_u32_e32 vcc, v3, v2
	s_nop 1
	v_cndmask_b32_e32 v4, v4, v5, vcc
	v_mul_lo_u32 v3, v2, v4
	v_add_u32_e32 v2, v3, v2
	v_mov_b32_e32 v248, v2
	v_cmp_ne_u32_e32 vcc, v6, v2
	v_mov_b64_e32 v[2:3], s[10:11]
	s_and_saveexec_b64 s[8:9], vcc
	s_cbranch_execz .LBB0_128
	v_mov_b32_e32 v2, 0
	global_load_dword v3, v2, s[98:99] sc1
	s_mov_b64 s[16:17], 0
	s_waitcnt vmcnt(0)
	v_cmp_lt_u32_e32 vcc, v3, v248
	s_and_saveexec_b64 s[14:15], vcc
	s_cbranch_execz .LBB0_127
	s_add_u32 s12, s76, 0x200
	s_addc_u32 s13, s77, 0
	s_mov_b32 s0, 1
	s_branch .LBB0_120

.LBB0_132:
	s_or_b64 exec, exec, s[10:11]
	s_waitcnt vmcnt(1)

.LBB0_869:
	s_or_b64 exec, exec, s[12:13]
	v_cvt_f32_u32_e32 v5, v2
	s_waitcnt vmcnt(0)
	v_readfirstlane_b32 s0, v4
	s_add_u32 s12, s76, 0x3500
	s_addc_u32 s13, s77, 0
	s_add_u32 s98, s76, 0x3400
	s_addc_u32 s99, s77, 0
	v_rcp_iflag_f32_e32 v5, v5
	v_add_u32_e32 v3, s0, v3
	v_add_u32_e32 v6, 1, v3
	s_mov_b64 s[14:15], 0
	v_mul_f32_e32 v4, 0x4f7ffffe, v5
	v_cvt_u32_f32_e32 v4, v4
	v_sub_u32_e32 v5, 0, v2
	v_mul_lo_u32 v5, v5, v4
	v_mul_hi_u32 v5, v4, v5
	v_add_u32_e32 v4, v4, v5
	v_mul_hi_u32 v4, v3, v4
	v_mul_lo_u32 v5, v4, v2
	v_sub_u32_e32 v3, v3, v5
	v_add_u32_e32 v7, 1, v4
	v_cmp_ge_u32_e32 vcc, v3, v2
	v_sub_u32_e32 v5, v3, v2
	s_nop 0
	v_cndmask_b32_e32 v4, v4, v7, vcc
	v_cndmask_b32_e32 v3, v3, v5, vcc
	v_add_u32_e32 v5, 1, v4
	v_cmp_ge_u32_e32 vcc, v3, v2
	s_nop 1
	v_cndmask_b32_e32 v4, v4, v5, vcc
	v_mul_lo_u32 v3, v2, v4
	v_add_u32_e32 v2, v3, v2
	v_mov_b32_e32 v248, v2
	v_cmp_ne_u32_e32 vcc, v6, v2
	v_mov_b64_e32 v[2:3], s[12:13]
	s_and_saveexec_b64 s[10:11], vcc
	s_cbranch_execz .LBB0_881
	v_mov_b32_e32 v2, 0
	global_load_dword v3, v2, s[98:99] sc1
	s_mov_b64 s[18:19], 0
	s_waitcnt vmcnt(0)
	v_cmp_lt_u32_e32 vcc, v3, v248
	s_and_saveexec_b64 s[16:17], vcc
	s_cbranch_execz .LBB0_880
	s_add_u32 s14, s76, 0x200
	s_addc_u32 s15, s77, 0
	s_mov_b32 s0, 1
	s_branch .LBB0_873

.LBB0_885:
	s_or_b64 exec, exec, s[12:13]
	s_waitcnt vmcnt(1)
